# barrier release by plain stores to four copies of the XCD generation word (16 pollers per copy)
# speedup vs baseline: 1.0089x; 1.0089x over previous
.Lbar_local:
	s_waitcnt vmcnt(0) lgkmcnt(0)
	v_add_u32_e32 v2, 1, v3
	v_readlane_b32 s4, v253, 8
	v_readlane_b32 s5, v253, 9
	s_nop 4
	global_store_dword v131, v2, s[4:5]
	v_mov_b32_e32 v3, 0x80
	global_store_dword v3, v2, s[4:5]
	s_sub_u32 s4, s4, 0x1000
	s_subb_u32 s5, s5, 0
	global_store_dword v3, v2, s[4:5]
	s_sub_u32 s4, s4, 0x1000
	s_subb_u32 s5, s5, 0
	global_store_dword v3, v2, s[4:5]
	buffer_inv sc1
	s_waitcnt vmcnt(0)
	s_branch .LBB0_61

.LBB0_58:
	s_or_b64 exec, exec, s[4:5]
	s_mov_b64 s[4:5], exec
	v_mbcnt_lo_u32_b32 v2, s4, 0
	v_mbcnt_hi_u32_b32 v2, s5, v2
	v_cmp_eq_u32_e32 vcc, 0, v2
	s_waitcnt vmcnt(0)
	s_and_saveexec_b64 s[6:7], vcc
	s_cbranch_execz .LBB0_60
	v_add_u32_e32 v2, 1, v9
	v_readlane_b32 s4, v253, 8
	v_readlane_b32 s5, v253, 9
	s_nop 4
	global_store_dword v131, v2, s[4:5]
	v_mov_b32_e32 v3, 0x80
	global_store_dword v3, v2, s[4:5]
	s_sub_u32 s4, s4, 0x1000
	s_subb_u32 s5, s5, 0
	global_store_dword v3, v2, s[4:5]
	s_sub_u32 s4, s4, 0x1000
	s_subb_u32 s5, s5, 0
	global_store_dword v3, v2, s[4:5]
